# RG-LRU: next chunk's prefetch loads issued spread through the gate stage instead of back-to-back before the conv barrier (on top of the S5 blocked scan)
# speedup vs baseline: 1.0065x; 1.0019x over previous
; #define LAS __attribute__((address_space(3)))
; __device__ __forceinline__ unsigned cvt_pk_bf16(float lo, float hi) { unsigned r; asm("v_cvt_pk_bf16_f32 %0, %1, %2" : "=v"(r) : "v"(lo), "v"(hi)); return r; }
; __device__ __forceinline__ void lru_item(const Args& a, LAS unsigned char* lds, bool sample, int b, int head, int q, int tid, int lane, int wave) {
;     ...
;         for (int chk = 0; chk < 8; ++chk) {
;             const int R0 = b * SEQ + chk * 256, r0 = rg * 8;
; #pragma unroll
;             for (int rr = 0; rr < 8; ++rr) {
;                 const f32x4 xc = cb + cw0 * xin[rr] + cw1 * xin[rr + 1] + cw2 * xin[rr + 2] + cw3 * xin[rr + 3];
;                 u32x2 w; w.x = cvt_pk_bf16(xc[0], xc[1]); w.y = cvt_pk_bf16(xc[2], xc[3]);
;                 *(LAS u32x2*)(XC + (r0 + rr) * XC_PITCH + 8 * cq) = w;
;                 if ((cq >> 2) == q) *(LAS f32x4*)(XCF + (r0 + rr) * 16 + 4 * (cq & 3)) = xc;
;             }
;             const u32x4 gw = ggn;
;             if (chk < 7) {
;                 const float* p = XL + (size_t)(R0 + 256 + r0 - 3) * DH + cch;
; #pragma unroll
;                 for (int i = 0; i < 11; ++i) xin[i] = *(const f32x4*)(p + (size_t)i * DH);
;                 ggn = *(const u32x4*)(GG + (size_t)(R0 + 256 + er) * DH + ch0 + 8 * eh);
;             }
;             __syncthreads();
.LBB0_672:
	v_pk_fma_f32 v[50:51], v[32:33], v[88:89], v[36:37]
	v_pk_fma_f32 v[52:53], v[30:31], v[86:87], v[34:35]
	v_pk_fma_f32 v[50:51], v[28:29], v[84:85], v[50:51]
	v_pk_fma_f32 v[52:53], v[26:27], v[82:83], v[52:53]
	v_pk_fma_f32 v[50:51], v[24:25], v[80:81], v[50:51]
	v_pk_fma_f32 v[86:87], v[22:23], v[78:79], v[52:53]
	s_waitcnt vmcnt(8)
	v_pk_fma_f32 v[52:53], v[20:21], v[72:73], v[50:51]
	v_pk_fma_f32 v[50:51], v[18:19], v[70:71], v[86:87]
	v_cvt_pk_bf16_f32 v87, v52, v53
	s_nop 0
	v_cvt_pk_bf16_f32 v86, v50, v51
	ds_write_b64 v175, v[86:87]
	s_and_saveexec_b64 s[36:37], s[8:9]
	v_add_u32_e32 v86, v137, v138
	ds_write_b128 v86, v[50:53] offset:36864
	s_or_b64 exec, exec, s[36:37]
	v_pk_fma_f32 v[50:51], v[32:33], v[84:85], v[36:37]
	v_pk_fma_f32 v[52:53], v[30:31], v[82:83], v[34:35]
	v_pk_fma_f32 v[50:51], v[28:29], v[80:81], v[50:51]
	v_pk_fma_f32 v[52:53], v[26:27], v[78:79], v[52:53]
	v_pk_fma_f32 v[50:51], v[24:25], v[72:73], v[50:51]
	v_pk_fma_f32 v[82:83], v[22:23], v[70:71], v[52:53]
	s_waitcnt vmcnt(7)
	v_pk_fma_f32 v[52:53], v[20:21], v[68:69], v[50:51]
	v_pk_fma_f32 v[50:51], v[18:19], v[66:67], v[82:83]
	v_cvt_pk_bf16_f32 v83, v52, v53
	s_nop 0
	v_cvt_pk_bf16_f32 v82, v50, v51
	ds_write_b64 v176, v[82:83]
	s_and_saveexec_b64 s[36:37], s[8:9]
	v_add_u32_e32 v82, v137, v148
	ds_write_b128 v82, v[50:53] offset:36864
	s_or_b64 exec, exec, s[36:37]
	v_pk_fma_f32 v[50:51], v[32:33], v[80:81], v[36:37]
	v_pk_fma_f32 v[52:53], v[30:31], v[78:79], v[34:35]
	v_pk_fma_f32 v[50:51], v[28:29], v[72:73], v[50:51]
	v_pk_fma_f32 v[52:53], v[26:27], v[70:71], v[52:53]
	v_pk_fma_f32 v[50:51], v[24:25], v[68:69], v[50:51]
	v_pk_fma_f32 v[78:79], v[22:23], v[66:67], v[52:53]
	s_waitcnt vmcnt(6)
	v_pk_fma_f32 v[52:53], v[20:21], v[64:65], v[50:51]
	v_pk_fma_f32 v[50:51], v[18:19], v[62:63], v[78:79]
	v_cvt_pk_bf16_f32 v79, v52, v53
	s_nop 0
	v_cvt_pk_bf16_f32 v78, v50, v51
	ds_write_b64 v176, v[78:79] offset:144
	s_and_saveexec_b64 s[36:37], s[8:9]
	v_add_u32_e32 v78, v137, v149
	ds_write_b128 v78, v[50:53] offset:36864
	s_or_b64 exec, exec, s[36:37]
	v_pk_fma_f32 v[50:51], v[32:33], v[72:73], v[36:37]
	v_pk_fma_f32 v[52:53], v[30:31], v[70:71], v[34:35]
	v_pk_fma_f32 v[50:51], v[28:29], v[68:69], v[50:51]
	v_pk_fma_f32 v[52:53], v[26:27], v[66:67], v[52:53]
	v_pk_fma_f32 v[50:51], v[24:25], v[64:65], v[50:51]
	v_pk_fma_f32 v[70:71], v[22:23], v[62:63], v[52:53]
	s_waitcnt vmcnt(5)
	v_pk_fma_f32 v[52:53], v[20:21], v[60:61], v[50:51]
	v_pk_fma_f32 v[50:51], v[18:19], v[58:59], v[70:71]
	v_cvt_pk_bf16_f32 v71, v52, v53
	s_nop 0
	v_cvt_pk_bf16_f32 v70, v50, v51
	ds_write_b64 v176, v[70:71] offset:288
	s_and_saveexec_b64 s[36:37], s[8:9]
	v_add_u32_e32 v70, v137, v150
	ds_write_b128 v70, v[50:53] offset:36864
	s_or_b64 exec, exec, s[36:37]
	v_pk_fma_f32 v[50:51], v[32:33], v[68:69], v[36:37]
	v_pk_fma_f32 v[52:53], v[30:31], v[66:67], v[34:35]
	v_pk_fma_f32 v[50:51], v[28:29], v[64:65], v[50:51]
	v_pk_fma_f32 v[52:53], v[26:27], v[62:63], v[52:53]
	v_pk_fma_f32 v[50:51], v[24:25], v[60:61], v[50:51]
	v_pk_fma_f32 v[66:67], v[22:23], v[58:59], v[52:53]
	s_waitcnt vmcnt(4)
	v_pk_fma_f32 v[52:53], v[20:21], v[40:41], v[50:51]
	v_pk_fma_f32 v[50:51], v[18:19], v[38:39], v[66:67]
	v_cvt_pk_bf16_f32 v67, v52, v53
	s_nop 0
	v_cvt_pk_bf16_f32 v66, v50, v51
	ds_write_b64 v176, v[66:67] offset:432
	s_and_saveexec_b64 s[36:37], s[8:9]
	v_add_u32_e32 v66, v137, v151
	ds_write_b128 v66, v[50:53] offset:36864
	s_or_b64 exec, exec, s[36:37]
	v_pk_fma_f32 v[50:51], v[32:33], v[64:65], v[36:37]
	v_pk_fma_f32 v[52:53], v[30:31], v[62:63], v[34:35]
	v_pk_fma_f32 v[50:51], v[28:29], v[60:61], v[50:51]
	v_pk_fma_f32 v[52:53], v[26:27], v[58:59], v[52:53]
	v_pk_fma_f32 v[50:51], v[24:25], v[40:41], v[50:51]
	v_pk_fma_f32 v[62:63], v[22:23], v[38:39], v[52:53]
	s_waitcnt vmcnt(3)
	v_pk_fma_f32 v[52:53], v[20:21], v[48:49], v[50:51]
	v_pk_fma_f32 v[50:51], v[18:19], v[46:47], v[62:63]
	v_cvt_pk_bf16_f32 v63, v52, v53
	s_nop 0
	v_cvt_pk_bf16_f32 v62, v50, v51
	ds_write_b64 v176, v[62:63] offset:576
	s_and_saveexec_b64 s[36:37], s[8:9]
	v_add_u32_e32 v62, v137, v152
	ds_write_b128 v62, v[50:53] offset:36864
	s_or_b64 exec, exec, s[36:37]
	v_pk_fma_f32 v[50:51], v[32:33], v[60:61], v[36:37]
	v_pk_fma_f32 v[52:53], v[30:31], v[58:59], v[34:35]
	v_pk_fma_f32 v[50:51], v[28:29], v[40:41], v[50:51]
	v_pk_fma_f32 v[52:53], v[26:27], v[38:39], v[52:53]
	v_pk_fma_f32 v[50:51], v[24:25], v[48:49], v[50:51]
	v_pk_fma_f32 v[58:59], v[22:23], v[46:47], v[52:53]
	s_waitcnt vmcnt(2)
	v_pk_fma_f32 v[52:53], v[20:21], v[44:45], v[50:51]
	v_pk_fma_f32 v[50:51], v[18:19], v[42:43], v[58:59]
	v_cvt_pk_bf16_f32 v59, v52, v53
	s_nop 0
	v_cvt_pk_bf16_f32 v58, v50, v51
	ds_write_b64 v176, v[58:59] offset:720
	s_and_saveexec_b64 s[36:37], s[8:9]
	v_add_u32_e32 v58, v137, v153
	ds_write_b128 v58, v[50:53] offset:36864
	s_or_b64 exec, exec, s[36:37]
	v_pk_fma_f32 v[40:41], v[32:33], v[40:41], v[36:37]
	v_pk_fma_f32 v[38:39], v[30:31], v[38:39], v[34:35]
	v_pk_fma_f32 v[40:41], v[28:29], v[48:49], v[40:41]
	v_pk_fma_f32 v[38:39], v[26:27], v[46:47], v[38:39]
	v_pk_fma_f32 v[40:41], v[24:25], v[44:45], v[40:41]
	v_pk_fma_f32 v[38:39], v[22:23], v[42:43], v[38:39]
	s_waitcnt vmcnt(2)
	v_pk_fma_f32 v[40:41], v[20:21], v[56:57], v[40:41]
	v_pk_fma_f32 v[38:39], v[18:19], v[54:55], v[38:39]
	v_cvt_pk_bf16_f32 v43, v40, v41
	s_nop 0
	v_cvt_pk_bf16_f32 v42, v38, v39
	ds_write_b64 v176, v[42:43] offset:864
	s_and_saveexec_b64 s[36:37], s[8:9]
	v_add_u32_e32 v42, v137, v154
	ds_write_b128 v42, v[38:41] offset:36864
	s_or_b64 exec, exec, s[36:37]
	v_add_u32_e32 v186, 0x9000, v155
	v_add_u32_e32 v183, 0xd000, v155
	v_add_u32_e32 v184, 0x9000, v161
	v_add_u32_e32 v185, 0xd000, v161
	s_waitcnt lgkmcnt(0)
	s_barrier
; #define LAS __attribute__((address_space(3)))
; __device__ __forceinline__ float fexp(float x) { return __builtin_amdgcn_exp2f(x * 1.44269504089f); }
; __device__ __forceinline__ float fsigmoid(float x) { return __builtin_amdgcn_rcpf(1.0f + fexp(-x)); }
; __device__ __forceinline__ void lru_item(const Args& a, LAS unsigned char* lds, bool sample, int b, int head, int q, int tid, int lane, int wave) {
;     ...
;             if (chk < 7) {
;                 const float* p = XL + (size_t)(R0 + 256 + r0 - 3) * DH + cch;
; #pragma unroll
;                 for (int i = 0; i < 11; ++i) xin[i] = *(const f32x4*)(p + (size_t)i * DH);
;                 ggn = *(const u32x4*)(GG + (size_t)(R0 + 256 + er) * DH + ch0 + 8 * eh);
;     ...
; #pragma unroll
;             for (int tt = 0; tt < 2; ++tt) {
;                 const int tile = 2 * wave + tt;
;                 f32x4 ar = (f32x4){0.f, 0.f, 0.f, 0.f}, ax = ar;
; #pragma unroll
;                 for (int ks = 0; ks < 2; ++ks) {
;                     const bf16x8 af = *(const LAS bf16x8*)(XC + (16 * tile + fr) * XC_PITCH + 64 * ks + 16 * fq);
;                     ar = __builtin_amdgcn_mfma_f32_16x16x32_bf16(af, Bf[0][ks], ar, 0, 0, 0);
;                     ax = __builtin_amdgcn_mfma_f32_16x16x32_bf16(af, Bf[1][ks], ax, 0, 0, 0);
;                 }
; #pragma unroll
;                 for (int r4 = 0; r4 < 4; ++r4) {
;                     const int rr = 16 * tile + 4 * fq + r4;
;                     const float xcv = XCF[rr * 16 + fr];
;                     const float rg_ = fsigmoid(ar[r4] + ba), ig = fsigmoid(ax[r4] + bx_);
;                     const float la = -8.0f * rg_ * spl;
;                     const float av = fexp(la); AA[rr * 16 + fr] = av; BX[rr * 16 + fr] = __builtin_amdgcn_sqrtf(fmaxf(fmaf(-av, av, 1.0f), 0.f)) * (ig * xcv);
;                 }
;             }
;             __syncthreads();
	ds_read_b128 v[118:121], v177
	ds_read_b32 v108, v155 offset:36992
	ds_read_b128 v[126:129], v177 offset:64
	s_waitcnt lgkmcnt(2)
	v_mfma_f32_16x16x32_bf16 v[122:125], v[118:121], v[2:5], 0
	v_mov_b32_e32 v187, v140
	s_waitcnt lgkmcnt(0)
	v_mfma_f32_16x16x32_bf16 v[122:125], v[126:129], v[14:17], v[122:125]
	v_mfma_f32_16x16x32_bf16 v[118:121], v[118:121], v[6:9], 0
	v_add_u32_e32 v38, s30, v182
	v_ashrrev_i32_e32 v39, 31, v38
	v_lshlrev_b64 v[38:39], 12, v[38:39]
	v_lshl_add_u64 v[50:51], v[110:111], 0, v[38:39]
	v_add_co_u32_e32 v38, vcc, 0x1000, v50
	v_add_u32_e32 v52, s30, v181
	s_nop 0
	v_addc_co_u32_e32 v39, vcc, 0, v51, vcc
	global_load_dwordx4 v[86:89], v[50:51], off
	s_nop 6
	v_add_f32_e32 v122, v97, v122
	v_mul_f32_e32 v122, 0xbfb8aa3b, v122
	v_exp_f32_e32 v122, v122
	v_mfma_f32_16x16x32_bf16 v[118:121], v[126:129], v[10:13], v[118:121]
	ds_read2_b32 v[126:127], v186 offset1:16
	v_add_f32_e32 v123, v97, v123
	v_add_f32_e32 v122, 1.0, v122
	v_rcp_f32_e32 v122, v122
	v_mul_f32_e32 v123, 0xbfb8aa3b, v123
	s_nop 2
	v_add_f32_e32 v118, v93, v118
	v_mul_f32_e32 v118, 0xbfb8aa3b, v118
	v_mul_f32_e32 v122, 0xc1000000, v122
	v_mul_f32_e32 v122, v180, v122
	global_load_dwordx4 v[82:85], v[38:39], off
	v_mul_f32_e32 v122, 0x3fb8aa3b, v122
	v_exp_f32_e32 v118, v118
	v_exp_f32_e32 v122, v122
	v_exp_f32_e32 v123, v123
	v_add_f32_e32 v119, v93, v119
	v_add_f32_e32 v118, 1.0, v118
	v_fma_f32 v128, -v122, v122, 1.0
	v_rcp_f32_e32 v118, v118
	v_max_f32_e32 v128, 0, v128
	v_sqrt_f32_e32 v128, v128
	v_mul_f32_e32 v119, 0xbfb8aa3b, v119
	s_waitcnt lgkmcnt(0)
	v_mul_f32_e32 v118, v126, v118
	v_exp_f32_e32 v119, v119
	v_mul_f32_e32 v118, v118, v128
	v_add_co_u32_e32 v38, vcc, 0x2000, v50
	v_ashrrev_i32_e32 v53, 31, v52
	s_nop 0
	v_addc_co_u32_e32 v39, vcc, 0, v51, vcc
	v_add_co_u32_e32 v40, vcc, 0x3000, v50
	v_lshlrev_b64 v[52:53], 11, v[52:53]
	s_nop 0
	v_addc_co_u32_e32 v41, vcc, 0, v51, vcc
	global_load_dwordx4 v[78:81], v[38:39], off
	ds_write_b32 v156, v118
	v_add_f32_e32 v118, 1.0, v123
	v_rcp_f32_e32 v118, v118
	v_add_f32_e32 v124, v97, v124
	v_add_f32_e32 v119, 1.0, v119
	v_mul_f32_e32 v124, 0xbfb8aa3b, v124
	v_mul_f32_e32 v118, 0xc1000000, v118
	v_mul_f32_e32 v118, v180, v118
	v_mul_f32_e32 v118, 0x3fb8aa3b, v118
	v_exp_f32_e32 v118, v118
	v_rcp_f32_e32 v119, v119
	v_exp_f32_e32 v124, v124
	v_add_f32_e32 v120, v93, v120
	v_fma_f32 v123, -v118, v118, 1.0
	ds_write2_b32 v183, v122, v118 offset1:16
	global_load_dwordx4 v[70:73], v[40:41], off
	v_mul_f32_e32 v118, v127, v119
	v_add_f32_e32 v119, 1.0, v124
	v_rcp_f32_e32 v119, v119
	v_max_f32_e32 v123, 0, v123
	v_sqrt_f32_e32 v123, v123
	v_mul_f32_e32 v120, 0xbfb8aa3b, v120
	v_mul_f32_e32 v119, 0xc1000000, v119
	v_mul_f32_e32 v119, v180, v119
	v_mul_f32_e32 v119, 0x3fb8aa3b, v119
	v_exp_f32_e32 v120, v120
	v_exp_f32_e32 v119, v119
	v_mul_f32_e32 v118, v118, v123
	ds_write_b32 v157, v118
	v_add_f32_e32 v118, 1.0, v120
	ds_write_b32 v155, v119 offset:53376
	v_add_co_u32_e32 v38, vcc, 0x4000, v50
	v_lshl_add_u64 v[52:53], v[112:113], 0, v[52:53]
	s_nop 0
	v_addc_co_u32_e32 v39, vcc, 0, v51, vcc
	v_add_co_u32_e32 v40, vcc, 0x5000, v50
	s_nop 0
	v_addc_co_u32_e32 v41, vcc, 0, v51, vcc
	global_load_dwordx4 v[66:69], v[38:39], off
	v_fma_f32 v119, -v119, v119, 1.0
	v_rcp_f32_e32 v118, v118
	v_max_f32_e32 v119, 0, v119
	v_add_f32_e32 v120, v97, v125
	v_sqrt_f32_e32 v119, v119
	v_mul_f32_e32 v120, 0xbfb8aa3b, v120
	v_exp_f32_e32 v120, v120
	v_mul_f32_e32 v108, v118, v108
	v_mul_f32_e32 v108, v108, v119
	ds_write_b32 v158, v108
	v_add_f32_e32 v108, 1.0, v120
	v_rcp_f32_e32 v108, v108
	v_add_f32_e32 v118, v93, v121
	v_mul_f32_e32 v118, 0xbfb8aa3b, v118
	v_exp_f32_e32 v118, v118
	global_load_dwordx4 v[62:65], v[40:41], off
	v_mul_f32_e32 v108, 0xc1000000, v108
	v_mul_f32_e32 v108, v180, v108
	v_mul_f32_e32 v108, 0x3fb8aa3b, v108
	v_exp_f32_e32 v108, v108
	ds_read_b32 v119, v159 offset:36864
	v_add_f32_e32 v118, 1.0, v118
	v_rcp_f32_e32 v118, v118
	v_fma_f32 v120, -v108, v108, 1.0
	v_max_f32_e32 v120, 0, v120
	v_sqrt_f32_e32 v120, v120
	ds_write_b32 v159, v108 offset:53248
	s_waitcnt lgkmcnt(1)
	v_mul_f32_e32 v108, v118, v119
	v_mul_f32_e32 v108, v108, v120
	ds_write_b32 v160, v108
	v_add_co_u32_e32 v38, vcc, 0x6000, v50
	s_nop 0
	v_addc_co_u32_e32 v39, vcc, 0, v51, vcc
	v_add_co_u32_e32 v40, vcc, 0x7000, v50
	s_nop 0
	v_addc_co_u32_e32 v41, vcc, 0, v51, vcc
	v_add_co_u32_e32 v42, vcc, 0x8000, v50
	global_load_dwordx4 v[58:61], v[38:39], off
	ds_read_b128 v[118:121], v178
	ds_read_b32 v108, v161 offset:36992
	ds_read_b128 v[126:129], v178 offset:64
	s_waitcnt lgkmcnt(2)
	v_mfma_f32_16x16x32_bf16 v[122:125], v[118:121], v[2:5], 0
	s_waitcnt lgkmcnt(0)
	v_mfma_f32_16x16x32_bf16 v[122:125], v[126:129], v[14:17], v[122:125]
	v_mfma_f32_16x16x32_bf16 v[118:121], v[118:121], v[6:9], 0
	s_nop 6
	v_add_f32_e32 v122, v97, v122
	v_mul_f32_e32 v122, 0xbfb8aa3b, v122
	v_exp_f32_e32 v122, v122
	v_mfma_f32_16x16x32_bf16 v[118:121], v[126:129], v[10:13], v[118:121]
	ds_read2_b32 v[126:127], v184 offset1:16
	v_add_f32_e32 v123, v97, v123
	s_nop 0
	global_load_dwordx4 v[38:41], v[40:41], off
	v_add_f32_e32 v122, 1.0, v122
	v_rcp_f32_e32 v122, v122
	v_mul_f32_e32 v123, 0xbfb8aa3b, v123
	s_nop 2
	v_add_f32_e32 v118, v93, v118
	v_mul_f32_e32 v118, 0xbfb8aa3b, v118
	v_mul_f32_e32 v122, 0xc1000000, v122
	v_mul_f32_e32 v122, v180, v122
	v_mul_f32_e32 v122, 0x3fb8aa3b, v122
	v_exp_f32_e32 v118, v118
	v_exp_f32_e32 v122, v122
	v_exp_f32_e32 v123, v123
	v_add_f32_e32 v119, v93, v119
	v_add_f32_e32 v118, 1.0, v118
	v_fma_f32 v128, -v122, v122, 1.0
	v_addc_co_u32_e32 v43, vcc, 0, v51, vcc
	v_add_co_u32_e32 v44, vcc, 0x9000, v50
	s_nop 0
	v_addc_co_u32_e32 v45, vcc, 0, v51, vcc
	v_add_co_u32_e32 v50, vcc, 0xa000, v50
	global_load_dwordx4 v[46:49], v[42:43], off
	v_rcp_f32_e32 v118, v118
	v_max_f32_e32 v128, 0, v128
	v_sqrt_f32_e32 v128, v128
	v_mul_f32_e32 v119, 0xbfb8aa3b, v119
	s_waitcnt lgkmcnt(0)
; #define LAS __attribute__((address_space(3)))
; __device__ __forceinline__ float fexp(float x) { return __builtin_amdgcn_exp2f(x * 1.44269504089f); }
; __device__ __forceinline__ float fsigmoid(float x) { return __builtin_amdgcn_rcpf(1.0f + fexp(-x)); }
; __device__ __forceinline__ void lru_item(const Args& a, LAS unsigned char* lds, bool sample, int b, int head, int q, int tid, int lane, int wave) {
;     ...
; #pragma unroll
;             for (int tt = 0; tt < 2; ++tt) {
;                 const int tile = 2 * wave + tt;
;                 f32x4 ar = (f32x4){0.f, 0.f, 0.f, 0.f}, ax = ar;
; #pragma unroll
;                 for (int ks = 0; ks < 2; ++ks) {
;                     const bf16x8 af = *(const LAS bf16x8*)(XC + (16 * tile + fr) * XC_PITCH + 64 * ks + 16 * fq);
;                     ar = __builtin_amdgcn_mfma_f32_16x16x32_bf16(af, Bf[0][ks], ar, 0, 0, 0);
;                     ax = __builtin_amdgcn_mfma_f32_16x16x32_bf16(af, Bf[1][ks], ax, 0, 0, 0);
;                 }
; #pragma unroll
;                 for (int r4 = 0; r4 < 4; ++r4) {
;                     const int rr = 16 * tile + 4 * fq + r4;
;                     const float xcv = XCF[rr * 16 + fr];
;                     const float rg_ = fsigmoid(ar[r4] + ba), ig = fsigmoid(ax[r4] + bx_);
;                     const float la = -8.0f * rg_ * spl;
;                     const float av = fexp(la); AA[rr * 16 + fr] = av; BX[rr * 16 + fr] = __builtin_amdgcn_sqrtf(fmaxf(fmaf(-av, av, 1.0f), 0.f)) * (ig * xcv);
;                 }
;             }
;             __syncthreads();
;             const int sn = tid & 15, sg = tid >> 4;
;             float av[8], bv[8];
;             const LAS float* ap = AA + (8 * sg) * 16 + sn; LAS float* bp = BX + (8 * sg) * 16 + sn;
;             asm volatile("" : "+v"(ap), "+v"(bp));
;             { float P = 1.f, h = 0.f;
; #pragma unroll
;               for (int i = 0; i < 8; ++i) { av[i] = ap[i * 16]; bv[i] = bp[i * 16]; }
; #pragma unroll
;               for (int i = 0; i < 8; ++i) { h = av[i] * h + bv[i]; P *= av[i]; }
;               SEGP[tid] = P; SEGH[tid] = h; }
	v_mul_f32_e32 v118, v126, v118
	v_exp_f32_e32 v119, v119
	v_mul_f32_e32 v118, v118, v128
	ds_write_b32 v164, v118
	v_add_f32_e32 v118, 1.0, v123
	v_rcp_f32_e32 v118, v118
	v_add_f32_e32 v124, v97, v124
	v_add_f32_e32 v119, 1.0, v119
	v_mul_f32_e32 v124, 0xbfb8aa3b, v124
	v_mul_f32_e32 v118, 0xc1000000, v118
	s_nop 0
	global_load_dwordx4 v[42:45], v[44:45], off
	v_mul_f32_e32 v118, v180, v118
	v_mul_f32_e32 v118, 0x3fb8aa3b, v118
	v_exp_f32_e32 v118, v118
	v_rcp_f32_e32 v119, v119
	v_exp_f32_e32 v124, v124
	v_add_f32_e32 v120, v93, v120
	v_fma_f32 v123, -v118, v118, 1.0
	ds_write2_b32 v185, v122, v118 offset1:16
	v_mul_f32_e32 v118, v127, v119
	v_add_f32_e32 v119, 1.0, v124
	v_rcp_f32_e32 v119, v119
	v_max_f32_e32 v123, 0, v123
	v_sqrt_f32_e32 v123, v123
	v_mul_f32_e32 v120, 0xbfb8aa3b, v120
	v_mul_f32_e32 v119, 0xc1000000, v119
	v_addc_co_u32_e32 v51, vcc, 0, v51, vcc
	global_load_dwordx4 v[54:57], v[50:51], off
	v_mul_f32_e32 v119, v180, v119
	v_mul_f32_e32 v119, 0x3fb8aa3b, v119
	v_exp_f32_e32 v120, v120
	v_exp_f32_e32 v119, v119
	v_mul_f32_e32 v118, v118, v123
	ds_write_b32 v165, v118
	v_add_f32_e32 v118, 1.0, v120
	ds_write_b32 v161, v119 offset:53376
	v_fma_f32 v119, -v119, v119, 1.0
	v_rcp_f32_e32 v118, v118
	v_max_f32_e32 v119, 0, v119
	v_add_f32_e32 v120, v97, v125
	v_sqrt_f32_e32 v119, v119
	v_mul_f32_e32 v120, 0xbfb8aa3b, v120
	v_exp_f32_e32 v120, v120
	s_nop 0
	global_load_dwordx4 v[50:53], v[52:53], off
	v_mul_f32_e32 v108, v118, v108
	v_mul_f32_e32 v108, v108, v119
	ds_write_b32 v166, v108
	v_add_f32_e32 v108, 1.0, v120
	v_rcp_f32_e32 v108, v108
	v_add_f32_e32 v118, v93, v121
	v_mul_f32_e32 v118, 0xbfb8aa3b, v118
	v_exp_f32_e32 v118, v118
	v_mul_f32_e32 v108, 0xc1000000, v108
	v_mul_f32_e32 v108, v180, v108
	v_mul_f32_e32 v108, 0x3fb8aa3b, v108
	v_exp_f32_e32 v108, v108
	ds_read_b32 v119, v167 offset:36864
	v_add_f32_e32 v118, 1.0, v118
	v_rcp_f32_e32 v118, v118
	v_fma_f32 v120, -v108, v108, 1.0
	v_max_f32_e32 v120, 0, v120
	v_sqrt_f32_e32 v120, v120
	ds_write_b32 v167, v108 offset:53248
	s_waitcnt lgkmcnt(1)
	v_mul_f32_e32 v108, v118, v119
	v_mul_f32_e32 v108, v108, v120
	ds_write_b32 v168, v108
	v_mov_b32_e32 v108, v139
	s_waitcnt lgkmcnt(0)
	s_barrier
	ds_read2_b32 v[132:133], v108 offset1:16
	ds_read2_b32 v[130:131], v187 offset1:16
	ds_read2_b32 v[128:129], v108 offset0:32 offset1:48
	ds_read2_b32 v[126:127], v187 offset0:32 offset1:48
	ds_read2_b32 v[124:125], v108 offset0:64 offset1:80
	ds_read2_b32 v[122:123], v187 offset0:64 offset1:80
	ds_read2_b32 v[118:119], v108 offset0:96 offset1:112
	ds_read2_b32 v[120:121], v187 offset0:96 offset1:112
	s_waitcnt lgkmcnt(6)
	v_fma_f32 v108, 0, v132, v130
	v_mul_f32_e32 v188, v132, v133
	v_fma_f32 v108, v108, v133, v131
	s_waitcnt lgkmcnt(5)
	v_mul_f32_e32 v188, v188, v128
	s_waitcnt lgkmcnt(4)
	v_fma_f32 v108, v108, v128, v126
	v_mul_f32_e32 v188, v188, v129
	v_fma_f32 v108, v108, v129, v127
	s_waitcnt lgkmcnt(3)
	v_mul_f32_e32 v188, v188, v124
	s_waitcnt lgkmcnt(2)
	v_fma_f32 v108, v108, v124, v122
	v_mul_f32_e32 v188, v188, v125
	v_fma_f32 v108, v108, v125, v123
	s_waitcnt lgkmcnt(1)
	v_mul_f32_e32 v188, v188, v118
	s_waitcnt lgkmcnt(0)
	v_fma_f32 v108, v108, v118, v120
	v_mul_f32_e32 v188, v188, v119
	v_fma_f32 v108, v108, v119, v121
	ds_write_b32 v141, v188
	ds_write_b32 v142, v108
	s_waitcnt lgkmcnt(0)
	s_barrier
	s_and_saveexec_b64 s[36:37], s[18:19]
	s_cbranch_execz .LBB0_690
; #define LAS __attribute__((address_space(3)))
; __device__ __forceinline__ void lru_item(const Args& a, LAS unsigned char* lds, bool sample, int b, int head, int q, int tid, int lane, int wave) {
;     ...
;             if (wave == 0 && lane < 16) {
;                 const LAS float* pp = SEGP + lane; const LAS float* hp = SEGH + lane; LAS float* cp = CAR + lane;
;                 asm volatile("" : "+v"(pp), "+v"(hp), "+v"(cp));
;                 float run = hcar;
; #pragma unroll
;                 for (int h2 = 0; h2 < 2; ++h2) {
;                     float sp_[16], sh_[16];
; #pragma unroll
;                     for (int s2 = 0; s2 < 16; ++s2) { sp_[s2] = pp[(16 * h2 + s2) * 16]; sh_[s2] = hp[(16 * h2 + s2) * 16]; }
; #pragma unroll
;                     for (int s2 = 0; s2 < 16; ++s2) { cp[(16 * h2 + s2) * 16] = run; run = sp_[s2] * run + sh_[s2]; }
;                 }
;                 hcar = run;
;             }
	v_mov_b32_e32 v108, v144
	v_mov_b32_e32 v211, v143
	v_mov_b32_e32 v222, v145
	ds_read2_b32 v[188:189], v211 offset1:16
	ds_read2_b32 v[190:191], v108 offset1:16
	ds_read2_b32 v[192:193], v211 offset0:32 offset1:48
	ds_read2_b32 v[194:195], v108 offset0:32 offset1:48
	ds_read2_b32 v[196:197], v211 offset0:64 offset1:80
	ds_read2_b32 v[198:199], v108 offset0:64 offset1:80
	ds_read2_b32 v[200:201], v211 offset0:96 offset1:112
	ds_read2_b32 v[202:203], v108 offset0:96 offset1:112
	ds_read2_b32 v[204:205], v211 offset0:128 offset1:144
	ds_read2_b32 v[206:207], v108 offset0:128 offset1:144
	ds_read2_b32 v[208:209], v211 offset0:160 offset1:176
	ds_read2_b32 v[212:213], v108 offset0:160 offset1:176
	ds_read2_b32 v[214:215], v211 offset0:192 offset1:208
	ds_read2_b32 v[216:217], v108 offset0:192 offset1:208
	ds_read2_b32 v[218:219], v211 offset0:224 offset1:240
	ds_read2_b32 v[220:221], v108 offset0:224 offset1:240
	s_waitcnt lgkmcnt(14)
	v_fma_f32 v188, v109, v188, v190
	v_fmac_f32_e32 v191, v188, v189
	ds_write2_b32 v222, v109, v188 offset1:16
	s_waitcnt lgkmcnt(13)
	v_fma_f32 v109, v191, v192, v194
	v_fmac_f32_e32 v195, v109, v193
	ds_write2_b32 v222, v191, v109 offset0:32 offset1:48
	s_waitcnt lgkmcnt(12)
	v_fma_f32 v109, v195, v196, v198
	v_fmac_f32_e32 v199, v109, v197
	ds_write2_b32 v222, v195, v109 offset0:64 offset1:80
	s_waitcnt lgkmcnt(11)
	v_fma_f32 v109, v199, v200, v202
	v_fmac_f32_e32 v203, v109, v201
	ds_write2_b32 v222, v199, v109 offset0:96 offset1:112
	s_waitcnt lgkmcnt(10)
	v_fma_f32 v109, v203, v204, v206
	v_fmac_f32_e32 v207, v109, v205
	ds_write2_b32 v222, v203, v109 offset0:128 offset1:144
	s_waitcnt lgkmcnt(9)
	v_fma_f32 v109, v207, v208, v212
	v_fmac_f32_e32 v213, v109, v209
	ds_write2_b32 v222, v207, v109 offset0:160 offset1:176
	s_waitcnt lgkmcnt(8)
	v_fma_f32 v109, v213, v214, v216
	v_fmac_f32_e32 v217, v109, v215
	ds_write2_b32 v222, v213, v109 offset0:192 offset1:208
	s_waitcnt lgkmcnt(7)
	v_fma_f32 v109, v217, v218, v220
	ds_write2_b32 v222, v217, v109 offset0:224 offset1:240
	v_fmac_f32_e32 v221, v109, v219
	v_add_u32_e32 v109, 0x400, v211
	ds_read2_b32 v[188:189], v109 offset1:16
	v_add_u32_e32 v108, 0x400, v108
	ds_read2_b32 v[190:191], v108 offset1:16
	ds_read2_b32 v[192:193], v109 offset0:32 offset1:48
	ds_read2_b32 v[194:195], v108 offset0:32 offset1:48
	ds_read2_b32 v[196:197], v109 offset0:64 offset1:80
	ds_read2_b32 v[198:199], v108 offset0:64 offset1:80
	ds_read2_b32 v[200:201], v109 offset0:96 offset1:112
	ds_read2_b32 v[202:203], v108 offset0:96 offset1:112
	ds_read2_b32 v[204:205], v109 offset0:128 offset1:144
	ds_read2_b32 v[206:207], v108 offset0:128 offset1:144
	ds_read2_b32 v[208:209], v109 offset0:160 offset1:176
	ds_read2_b32 v[212:213], v108 offset0:160 offset1:176
	ds_read2_b32 v[214:215], v109 offset0:192 offset1:208
	ds_read2_b32 v[216:217], v108 offset0:192 offset1:208
	ds_read2_b32 v[218:219], v109 offset0:224 offset1:240
	ds_read2_b32 v[108:109], v108 offset0:224 offset1:240
	s_waitcnt lgkmcnt(14)
	v_fma_f32 v188, v221, v188, v190
	v_add_u32_e32 v190, 0x400, v222
	v_fmac_f32_e32 v191, v188, v189
	ds_write2_b32 v190, v221, v188 offset1:16
	s_waitcnt lgkmcnt(13)
	v_fma_f32 v188, v191, v192, v194
	v_fmac_f32_e32 v195, v188, v193
	ds_write2_b32 v190, v191, v188 offset0:32 offset1:48
	s_waitcnt lgkmcnt(12)
	v_fma_f32 v188, v195, v196, v198
	v_fmac_f32_e32 v199, v188, v197
	ds_write2_b32 v190, v195, v188 offset0:64 offset1:80
	s_waitcnt lgkmcnt(11)
	v_fma_f32 v188, v199, v200, v202
	v_fmac_f32_e32 v203, v188, v201
	ds_write2_b32 v190, v199, v188 offset0:96 offset1:112
	s_waitcnt lgkmcnt(10)
	v_fma_f32 v188, v203, v204, v206
	v_fmac_f32_e32 v207, v188, v205
	ds_write2_b32 v190, v203, v188 offset0:128 offset1:144
	s_waitcnt lgkmcnt(9)
	v_fma_f32 v188, v207, v208, v212
	v_fmac_f32_e32 v213, v188, v209
	ds_write2_b32 v190, v207, v188 offset0:160 offset1:176
	s_waitcnt lgkmcnt(8)
	v_fma_f32 v188, v213, v214, v216
	v_fmac_f32_e32 v217, v188, v215
	s_waitcnt lgkmcnt(6)
	v_fma_f32 v108, v217, v218, v108
	v_fmac_f32_e32 v109, v108, v219
	ds_write2_b32 v190, v213, v188 offset0:192 offset1:208
	ds_write2_b32 v190, v217, v108 offset0:224 offset1:240
